# attention: one static s_setprio 1 for waves 4-7 (second query row of each iteration) for the whole phase
# baseline (speedup 1.0000x reference)
.LBB0_111:
	s_barrier
	v_readfirstlane_b32 s0, v156
	s_cmp_lt_u32 s0, 0x100
	s_cbranch_scc1 .Lattn_prio_skip
	s_setprio 1
.Lattn_prio_skip:
	s_lshl_b32 s0, s12, 6
	s_ashr_i32 s14, s12, 4
	s_and_b32 s13, s0, 0x3c0
	s_mov_b32 s5, 0x20200
	s_and_b32 s4, s11, 15
	s_mulk_i32 s4, 0x1d1
	v_and_b32_e32 v0, 63, v156
	v_bfe_u32 v1, v156, 6, 2
	v_lshrrev_b32_e32 v2, 8, v156
	v_sub_u32_e32 v3, v0, v1
	v_add_u32_e32 v3, -16, v3
	v_med3_i32 v4, v3, 0, 30
	v_lshlrev_b32_e32 v5, 3, v2
	v_mad_u32_u24 v6, v5, 31, v4
	v_add_lshl_u32 v6, v6, s4, 2
	v_lshlrev_b32_e32 v7, 2, v0
	v_mul_u32_u24_e32 v16, 0xf00, v1
	v_lshl_add_u32 v7, v5, 8, v7
	v_add3_u32 v7, v7, v16, s5
	v_cmp_eq_u32_e32 vcc, 0, v2
	v_add_u32_e32 v17, 0x2e8, v6
	v_add_u32_e32 v18, 0x364, v6
	v_lshl_add_u32 v19, v1, 8, 0
	v_cndmask_b32_e32 v17, v17, v18, vcc
	v_lshl_add_u32 v19, v0, 2, v19
	v_add_u32_e32 v18, 0x700, v7
	v_cndmask_b32_e32 v19, v19, v18, vcc
	global_load_dword v8, v6, s[64:65] offset:0
	global_load_dword v9, v6, s[64:65] offset:124
	global_load_dword v10, v6, s[64:65] offset:248
	global_load_dword v11, v6, s[64:65] offset:372
	global_load_dword v12, v6, s[64:65] offset:496
	global_load_dword v13, v6, s[64:65] offset:620
	global_load_dword v14, v6, s[64:65] offset:744
	global_load_dword v15, v17, s[64:65]
	s_lshl_b32 s2, s14, 8
	s_lshl_b32 s26, s13, 1
	s_add_i32 s2, s2, 0x8000
	v_lshl_add_u64 v[16:17], v[68:69], 0, s[26:27]
	v_ashrrev_i32_e32 v18, 3, v156
	v_add_u32_e32 v20, s2, v18
	v_ashrrev_i32_e32 v21, 31, v20
	v_lshlrev_b64 v[20:21], 12, v[20:21]
	v_lshl_add_u64 v[20:21], v[16:17], 0, v[20:21]
	s_mov_b32 s16, 0x40000
	global_load_dwordx4 v[24:27], v[20:21], off offset:2048
	v_add_co_u32_e32 v20, vcc, s16, v20
	s_nop 1
	v_addc_co_u32_e32 v21, vcc, 0, v21, vcc
	global_load_dwordx4 v[28:31], v[20:21], off offset:2048
	v_add_co_u32_e32 v20, vcc, s16, v20
	s_nop 1
	v_addc_co_u32_e32 v21, vcc, 0, v21, vcc
	global_load_dwordx4 v[32:35], v[20:21], off offset:2048
	v_add_co_u32_e32 v20, vcc, s16, v20
	s_nop 1
	v_addc_co_u32_e32 v21, vcc, 0, v21, vcc
	global_load_dwordx4 v[36:39], v[20:21], off offset:2048
	v_lshlrev_b32_e32 v22, 2, v18
	v_lshrrev_b32_e32 v23, 1, v18
	v_and_b32_e32 v1, 0xfffffe3, v18
	v_and_b32_e32 v22, 16, v22
	v_and_b32_e32 v23, 12, v23
	v_or3_b32 v1, v1, v22, v23
	v_lshrrev_b32_e32 v22, 4, v1
	v_and_b32_e32 v23, 15, v1
	v_lshlrev_b32_e32 v22, 11, v22
	v_lshl_add_u32 v22, v23, 4, v22
	v_lshl_add_u32 v1, v62, 4, v22
	s_ashr_i32 s3, s2, 31
	v_lshl_add_u64 v[16:17], s[2:3], 1, v[64:65]
	v_ashrrev_i32_e32 v18, 5, v156
	v_add_u32_e32 v20, s13, v18
	v_mad_i64_i32 v[20:21], s[16:17], v20, s23, v[16:17]
	s_mov_b32 s4, 0x120000
	global_load_dwordx4 v[40:43], v[20:21], off
	v_add_co_u32_e32 v20, vcc, s4, v20
	s_nop 1
	v_addc_co_u32_e32 v21, vcc, 0, v21, vcc
	global_load_dwordx4 v[44:47], v[20:21], off
	v_add_co_u32_e32 v20, vcc, s4, v20
	s_nop 1
	v_addc_co_u32_e32 v21, vcc, 0, v21, vcc
	global_load_dwordx4 v[48:51], v[20:21], off
	v_add_co_u32_e32 v20, vcc, s4, v20
	s_nop 1
	v_addc_co_u32_e32 v21, vcc, 0, v21, vcc
	global_load_dwordx4 v[52:55], v[20:21], off
	v_bfe_u32 v22, v66, 4, 2
	v_lshlrev_b32_e32 v22, 8, v22
	v_lshrrev_b32_e32 v16, 6, v66
	v_lshl_add_u32 v22, v16, 12, v22
	v_lshl_add_u32 v23, v18, 4, v22
	v_cmp_gt_u32_e64 s[2:3], 31, v3
	s_waitcnt vmcnt(8)
	v_mul_f32_e32 v8, 0x3fb8aa3b, v8
	v_cndmask_b32_e64 v8, 0, v8, s[2:3]
	v_mul_f32_e32 v9, 0x3fb8aa3b, v9
	v_cndmask_b32_e64 v9, 0, v9, s[2:3]
	v_mul_f32_e32 v10, 0x3fb8aa3b, v10
	v_cndmask_b32_e64 v10, 0, v10, s[2:3]
	v_mul_f32_e32 v11, 0x3fb8aa3b, v11
	v_cndmask_b32_e64 v11, 0, v11, s[2:3]
	v_mul_f32_e32 v12, 0x3fb8aa3b, v12
	v_cndmask_b32_e64 v12, 0, v12, s[2:3]
	v_mul_f32_e32 v13, 0x3fb8aa3b, v13
	v_cndmask_b32_e64 v13, 0, v13, s[2:3]
	v_mul_f32_e32 v14, 0x3fb8aa3b, v14
	v_cndmask_b32_e64 v14, 0, v14, s[2:3]
	v_mul_f32_e32 v15, 0x3fb8aa3b, v15
	v_cndmask_b32_e64 v15, 0, v15, s[2:3]
	ds_write_b32 v7, v8 offset:0
	ds_write_b32 v7, v9 offset:256
	ds_write_b32 v7, v10 offset:512
	ds_write_b32 v7, v11 offset:768
	ds_write_b32 v7, v12 offset:1024
	ds_write_b32 v7, v13 offset:1280
	ds_write_b32 v7, v14 offset:1536
	ds_write_b32 v19, v15
	s_waitcnt vmcnt(7)
	ds_write_b128 v1, v[24:27] offset:3072
	s_waitcnt vmcnt(6)
	ds_write_b128 v1, v[28:31] offset:11264
	s_waitcnt vmcnt(5)
	ds_write_b128 v1, v[32:35] offset:19456
	s_waitcnt vmcnt(4)
	ds_write_b128 v1, v[36:39] offset:27648
	s_waitcnt vmcnt(3)
	ds_write_b128 v23, v[40:43] offset:39936
	s_waitcnt vmcnt(2)
	ds_write_b128 v23, v[44:47] offset:40960
	s_waitcnt vmcnt(1)
	ds_write_b128 v23, v[48:51] offset:41984
	s_waitcnt vmcnt(0)
	ds_write_b128 v23, v[52:55] offset:43008

.LBB0_163:
	s_setprio 0
	v_readlane_b32 s36, v249, 38
	s_mov_b64 s[0:1], 0
	v_readlane_b32 s37, v249, 39
